# grid-barrier census: the 16 per-XCC counter loads of the one-time census poll issued together (immediate offsets off one base) with a single wait, instead of 16 serialised load+wait pairs
# baseline (speedup 1.0000x reference)
; __device__ __forceinline__ unsigned xb_ld(unsigned* p)              { return __hip_atomic_load(p, __ATOMIC_RELAXED, __HIP_MEMORY_SCOPE_AGENT); }
;     DI bf16_t* z() const { return (bf16_t*)(ws + WS_Z); }
; __device__ __forceinline__ void xcd_barrier_complete(unsigned* bar, unsigned x, unsigned& nloc, unsigned& nx) {
;     const unsigned G = gridDim.x * gridDim.y * gridDim.z;
;     unsigned sum, cnt, mine, sp = 0u;
;     for (;;) {
;         sum = 0u; cnt = 0u; mine = 0u;
; #pragma unroll
;         for (unsigned j = 0; j < 16; ++j) { const unsigned c = xb_ld(&bar[XB_XCNT(j)]); sum += c; cnt += (c > 0u) ? 1u : 0u; mine = (j == x) ? c : mine; }
;         if (sum == G) break;
;         __builtin_amdgcn_s_sleep(1);
;         if ((++sp & 255u) == 0u) { if (xb_ld(&bar[XB_TMO])) break; if (sp > XB_SPIN_CAP) { atomicAdd(&bar[XB_TMO], 1u); break; } }
;     }
;     nloc = mine > 0u ? mine : 1u; nx = cnt > 0u ? cnt : 1u;
; }
.LBB0_2099:
	v_readlane_b32 s10, v253, 1
	v_readlane_b32 s11, v253, 2
	s_mov_b64 s[16:17], -1
	s_waitcnt lgkmcnt(0)
	s_nop 4
	global_load_dword v0, v1, s[10:11] sc1
	global_load_dword v2, v1, s[10:11] offset:256 sc1
	global_load_dword v3, v1, s[10:11] offset:512 sc1
	global_load_dword v4, v1, s[10:11] offset:768 sc1
	global_load_dword v5, v1, s[10:11] offset:1024 sc1
	global_load_dword v6, v1, s[10:11] offset:1280 sc1
	global_load_dword v7, v1, s[10:11] offset:1536 sc1
	global_load_dword v8, v1, s[10:11] offset:1792 sc1
	global_load_dword v9, v1, s[10:11] offset:2048 sc1
	global_load_dword v10, v1, s[10:11] offset:2304 sc1
	global_load_dword v11, v1, s[10:11] offset:2560 sc1
	global_load_dword v12, v1, s[10:11] offset:2816 sc1
	global_load_dword v13, v1, s[10:11] offset:3072 sc1
	global_load_dword v14, v1, s[10:11] offset:3328 sc1
	global_load_dword v15, v1, s[10:11] offset:3584 sc1
	global_load_dword v16, v1, s[10:11] offset:3840 sc1
	s_mov_b64 s[10:11], -1
	s_waitcnt vmcnt(0)
	v_add_u32_e32 v17, v2, v0
	v_add_u32_e32 v17, v17, v3
	v_add_u32_e32 v17, v17, v4
	v_add_u32_e32 v17, v17, v5
	v_add_u32_e32 v17, v17, v6
	v_add_u32_e32 v17, v17, v7
	v_add_u32_e32 v17, v17, v8
	v_add_u32_e32 v17, v17, v9
	v_add_u32_e32 v17, v17, v10
	v_add_u32_e32 v17, v17, v11
	v_add_u32_e32 v17, v17, v12
	v_add_u32_e32 v17, v17, v13
	v_add_u32_e32 v17, v17, v14
	v_add_u32_e32 v17, v17, v15
	v_add_u32_e32 v17, v17, v16
	v_cmp_eq_u32_e32 vcc, s44, v17
	s_cbranch_vccnz .LBB0_2098
	s_and_b32 s10, s23, 0xff
	s_cmp_eq_u32 s10, 0
	s_mov_b64 s[10:11], -1
	s_mov_b64 s[42:43], -1
	s_sleep 1
	s_cbranch_scc1 .LBB0_2103
	s_and_b64 vcc, exec, s[42:43]
	s_cbranch_vccz .LBB0_2098
